# GEMM phase prologues: second group of stage loads issued before waiting for the first (one memory latency less per GEMM phase start), on top of P4 SG prefetch
# speedup vs baseline: 1.0248x; 1.0051x over previous
; #define PG8_STAGE(bufoff, gbase, voff) do { _Pragma("unroll") for (int _i = 0; _i < 2; ++_i) \
;         __builtin_amdgcn_global_load_lds((const unsigned*)((const char*)(gbase) + (voff)[_i]), (LAS unsigned*)(lds + (bufoff) + ldsw + _i * 8192), 16, 0, 0); } while (0)
; #define PG8_WAIT_V(n) asm volatile("s_waitcnt vmcnt(" #n ")" ::: "memory")
; #define PG8_BAR __builtin_amdgcn_s_barrier()
; template <class Epi>
; __device__ __forceinline__ void gemm_phase(LAS unsigned char* lds, const Gemm g, const StaticOrder& S, const Epi& E) {
;     ...
;     PG8_STAGE(PG8_SB(0, 0), cB, voffB); PG8_STAGE(PG8_SB(0, 1), cB + hsB, voffB); PG8_STAGE(PG8_SA(0, 0), cA, voffA); PG8_STAGE(PG8_SA(0, 1), cA + hsA, voffA);
;     if (wr == 1) PG8_BAR;
;     PG8_WAIT_V(2); PG8_BAR;
;     PG8_STAGE(PG8_SB(1, 0), cB + kstep, voffB); PG8_STAGE(PG8_SA(1, 0), cA + kstep, voffA); PG8_STAGE(PG8_SB(1, 1), cB + hsB + kstep, voffB);
;     PG8_WAIT_V(6); PG8_BAR;
.LBB0_250:
	s_lshl_b32 s1, s1, 5
	s_mov_b64 s[10:11], 0x80
	s_and_b32 s1, s1, 0x60
	s_add_i32 m0, s29, 0x18000
	v_lshl_add_u64 v[6:7], v[6:7], 0, s[10:11]
	s_lshl_b32 s5, s0, 13
	s_lshl_b32 s19, s1, 7
	global_load_lds_dwordx4 v[6:7], off
	v_lshl_add_u64 v[2:3], v[2:3], 0, s[10:11]
	s_add_i32 m0, s29, 0x1a000
	s_add_i32 s43, s29, 0x8000
	s_add_i32 s44, s29, 0xa000
	global_load_lds_dwordx4 v[2:3], off
	v_lshl_add_u64 v[0:1], v[0:1], 0, s[10:11]
	s_mov_b32 m0, s43
	s_add_u32 s20, s34, 0x80080
	global_load_lds_dwordx4 v[0:1], off
	v_lshl_add_u64 v[0:1], v[4:5], 0, s[10:11]
	s_mov_b32 m0, s44
	s_addc_u32 s21, s35, 0
	global_load_lds_dwordx4 v[0:1], off
	s_add_i32 m0, s29, 0x1c000
	v_lshl_add_u64 v[0:1], s[20:21], 0, v[130:131]
	global_load_lds_dwordx4 v[0:1], off
	v_lshl_add_u64 v[0:1], s[20:21], 0, v[134:135]
	s_add_i32 m0, s29, 0x1e000
	v_lshlrev_b32_e32 v3, 6, v198
	global_load_lds_dwordx4 v[0:1], off
	s_waitcnt vmcnt(8)
	s_barrier
	v_and_b32_e32 v0, 15, v198
	v_lshl_or_b32 v153, s0, 6, v0
	v_lshlrev_b32_e32 v1, 1, v11
	s_movk_i32 s0, 0x3c0
	v_lshl_or_b32 v0, v0, 6, v1
	v_and_b32_e32 v2, 32, v152
	v_and_or_b32 v1, v3, s0, v1
	v_bitop3_b32 v154, s19, v1, v2 bitop3:0xf6
	v_lshlrev_b32_e32 v1, 9, v198
	v_bitop3_b32 v0, v0, s5, v2 bitop3:0xde
	v_and_b32_e32 v1, 0x70000, v1
	v_lshlrev_b32_e32 v2, 12, v10
	v_or3_b32 v1, v8, v1, v2
	v_add_u32_e32 v138, v1, v9
	v_lshlrev_b32_e32 v1, 5, v12
	s_waitcnt vmcnt(6)
	s_cmpk_lt_u32 s18, 0x100
	v_and_b32_e32 v1, 0xf0000, v1
	s_cselect_b64 s[18:19], -1, 0
	v_or3_b32 v1, v8, v1, v2
	s_add_i32 s47, 0, 0x10000
	s_add_i32 s48, 0, 0x14000
	s_ashr_i32 s45, s63, 31
	s_ashr_i32 s46, s2, 31
	v_or_b32_e32 v155, s1, v11
	v_mov_b32_e32 v139, v137
	v_add_u32_e32 v140, v1, v9
	v_mov_b32_e32 v141, v137
	v_mov_b64_e32 v[142:143], 0x480
	v_mov_b64_e32 v[144:145], 0x47f
	v_add_u32_e32 v156, s47, v154
	v_add_u32_e32 v157, s48, v154
	v_add_u32_e32 v158, 0, v0
	s_barrier
	s_branch .LBB0_253

; #define PG8_STAGE(bufoff, gbase, voff) do { _Pragma("unroll") for (int _i = 0; _i < 2; ++_i) \
;         __builtin_amdgcn_global_load_lds((const unsigned*)((const char*)(gbase) + (voff)[_i]), (LAS unsigned*)(lds + (bufoff) + ldsw + _i * 8192), 16, 0, 0); } while (0)
; #define PG8_WAIT_V(n) asm volatile("s_waitcnt vmcnt(" #n ")" ::: "memory")
; #define PG8_BAR __builtin_amdgcn_s_barrier()
; template <class Epi>
; __device__ __forceinline__ void gemm_phase(LAS unsigned char* lds, const Gemm g, const StaticOrder& S, const Epi& E) {
;     ...
;     PG8_STAGE(PG8_SB(0, 0), cB, voffB); PG8_STAGE(PG8_SB(0, 1), cB + hsB, voffB); PG8_STAGE(PG8_SA(0, 0), cA, voffA); PG8_STAGE(PG8_SA(0, 1), cA + hsA, voffA);
;     if (wr == 1) PG8_BAR;
;     PG8_WAIT_V(2); PG8_BAR;
;     PG8_STAGE(PG8_SB(1, 0), cB + kstep, voffB); PG8_STAGE(PG8_SA(1, 0), cA + kstep, voffA); PG8_STAGE(PG8_SB(1, 1), cB + hsB + kstep, voffB);
;     PG8_WAIT_V(6); PG8_BAR;
.LBB0_566:
	s_lshl_b32 s5, s5, 5
	s_mov_b64 s[20:21], 0x80
	s_and_b32 s5, s5, 0x60
	s_add_i32 m0, s31, 0x18000
	v_lshl_add_u64 v[6:7], v[6:7], 0, s[20:21]
	s_lshl_b32 s24, s4, 13
	s_lshl_b32 s25, s5, 7
	global_load_lds_dwordx4 v[6:7], off
	v_lshl_add_u64 v[2:3], v[2:3], 0, s[20:21]
	s_add_i32 m0, s31, 0x1a000
	s_add_i32 s45, s31, 0x8000
	s_add_i32 s46, s31, 0xa000
	global_load_lds_dwordx4 v[2:3], off
	v_lshl_add_u64 v[0:1], v[0:1], 0, s[20:21]
	s_mov_b32 m0, s45
	s_add_u32 s22, s34, 0x20080
	global_load_lds_dwordx4 v[0:1], off
	v_lshl_add_u64 v[0:1], v[4:5], 0, s[20:21]
	s_mov_b32 m0, s46
	s_addc_u32 s23, s35, 0
	global_load_lds_dwordx4 v[0:1], off
	s_add_i32 m0, s31, 0x1c000
	v_lshl_add_u64 v[0:1], s[22:23], 0, v[164:165]
	global_load_lds_dwordx4 v[0:1], off
	v_lshl_add_u64 v[0:1], s[22:23], 0, v[160:161]
	s_add_i32 m0, s31, 0x1e000
	s_sext_i32_i8 s50, s0
	global_load_lds_dwordx4 v[0:1], off
	s_waitcnt vmcnt(8)
	s_barrier
	v_and_b32_e32 v0, 15, v198
	v_lshlrev_b32_e32 v1, 1, v11
	v_lshlrev_b32_e32 v2, 2, v198
	v_lshlrev_b32_e32 v3, 6, v198
	s_movk_i32 s0, 0x3c0
	v_lshl_or_b32 v182, s4, 6, v0
	v_lshl_or_b32 v0, v0, 6, v1
	v_and_b32_e32 v2, 32, v2
	v_and_or_b32 v1, v3, s0, v1
	v_bitop3_b32 v183, s25, v1, v2 bitop3:0xf6
	v_lshlrev_b32_e32 v1, 9, v198
	v_bitop3_b32 v0, v0, s24, v2 bitop3:0xde
	v_and_b32_e32 v1, 0x70000, v1
	v_lshlrev_b32_e32 v2, 12, v12
	v_or3_b32 v1, v9, v1, v2
	v_add_u32_e32 v168, v1, v10
	v_lshlrev_b32_e32 v1, 5, v8
	s_waitcnt vmcnt(6)
	s_cmpk_lt_u32 s1, 0x100
	v_and_b32_e32 v1, 0xf0000, v1
	s_cselect_b64 s[22:23], -1, 0
	v_or3_b32 v1, v9, v1, v2
	s_add_i32 s48, 0, 0x10000
	s_add_i32 s49, 0, 0x14000
	s_ashr_i32 s47, s63, 31
	v_or_b32_e32 v184, s5, v11
	v_mov_b32_e32 v169, v165
	v_add_u32_e32 v170, v1, v10
	v_mov_b32_e32 v171, v165
	v_mov_b64_e32 v[172:173], 0x240
	v_mov_b64_e32 v[174:175], 0x23f
	v_add_u32_e32 v185, s48, v183
	v_add_u32_e32 v186, s49, v183
	v_add_u32_e32 v187, 0, v0
	s_barrier
	s_branch .LBB0_569

; #define PG8_STAGE(bufoff, gbase, voff) do { _Pragma("unroll") for (int _i = 0; _i < 2; ++_i) \
;         __builtin_amdgcn_global_load_lds((const unsigned*)((const char*)(gbase) + (voff)[_i]), (LAS unsigned*)(lds + (bufoff) + ldsw + _i * 8192), 16, 0, 0); } while (0)
; #define PG8_WAIT_V(n) asm volatile("s_waitcnt vmcnt(" #n ")" ::: "memory")
; #define PG8_BAR __builtin_amdgcn_s_barrier()
; template <class Epi>
; __device__ __forceinline__ void gemm_phase(LAS unsigned char* lds, const Gemm g, const StaticOrder& S, const Epi& E) {
;     ...
;     PG8_STAGE(PG8_SB(0, 0), cB, voffB); PG8_STAGE(PG8_SB(0, 1), cB + hsB, voffB); PG8_STAGE(PG8_SA(0, 0), cA, voffA); PG8_STAGE(PG8_SA(0, 1), cA + hsA, voffA);
;     if (wr == 1) PG8_BAR;
;     PG8_WAIT_V(2); PG8_BAR;
;     PG8_STAGE(PG8_SB(1, 0), cB + kstep, voffB); PG8_STAGE(PG8_SA(1, 0), cA + kstep, voffA); PG8_STAGE(PG8_SB(1, 1), cB + hsB + kstep, voffB);
;     PG8_WAIT_V(6); PG8_BAR;
.LBB0_635:
	s_lshl_b32 s8, s8, 5
	s_and_b32 s24, s8, 0x60
	s_mov_b64 s[8:9], 0x80
	s_add_i32 m0, s31, 0x18000
	v_lshl_add_u64 v[6:7], v[6:7], 0, s[8:9]
	s_lshl_b32 s11, s10, 13
	s_lshl_b32 s25, s24, 7
	global_load_lds_dwordx4 v[6:7], off
	v_lshl_add_u64 v[2:3], v[2:3], 0, s[8:9]
	s_add_i32 m0, s31, 0x1a000
	s_add_i32 s47, s31, 0x8000
	s_add_i32 s48, s31, 0xa000
	global_load_lds_dwordx4 v[2:3], off
	v_lshl_add_u64 v[0:1], v[0:1], 0, s[8:9]
	s_mov_b32 m0, s47
	s_add_u32 s22, s36, 0x80080
	global_load_lds_dwordx4 v[0:1], off
	v_lshl_add_u64 v[0:1], v[4:5], 0, s[8:9]
	s_mov_b32 m0, s48
	s_addc_u32 s23, s37, 0
	global_load_lds_dwordx4 v[0:1], off
	s_add_i32 m0, s31, 0x1c000
	v_lshl_add_u64 v[0:1], s[22:23], 0, v[132:133]
	global_load_lds_dwordx4 v[0:1], off
	v_lshl_add_u64 v[0:1], s[22:23], 0, v[128:129]
	s_add_i32 m0, s31, 0x1e000
	s_sext_i32_i8 s52, s0
	global_load_lds_dwordx4 v[0:1], off
	s_waitcnt vmcnt(8)
	s_barrier
	v_and_b32_e32 v0, 15, v198
	v_lshlrev_b32_e32 v1, 1, v11
	v_lshlrev_b32_e32 v3, 6, v198
	s_movk_i32 s0, 0x3c0
	v_lshl_or_b32 v147, s10, 6, v0
	v_lshl_or_b32 v0, v0, 6, v1
	v_and_b32_e32 v2, 32, v146
	v_and_or_b32 v1, v3, s0, v1
	v_bitop3_b32 v148, s25, v1, v2 bitop3:0xf6
	v_lshlrev_b32_e32 v1, 9, v198
	v_bitop3_b32 v0, v0, s11, v2 bitop3:0xde
	v_and_b32_e32 v1, 0x70000, v1
	v_lshlrev_b32_e32 v2, 12, v12
	v_or3_b32 v1, v9, v1, v2
	v_add_u32_e32 v136, v1, v10
	v_lshlrev_b32_e32 v1, 5, v8
	s_waitcnt vmcnt(6)
	s_cmpk_lt_u32 s1, 0x100
	v_and_b32_e32 v1, 0xf0000, v1
	s_cselect_b64 s[10:11], -1, 0
	v_or3_b32 v1, v9, v1, v2
	s_add_i32 s50, 0, 0x10000
	s_add_i32 s51, 0, 0x14000
	s_ashr_i32 s49, s63, 31
	v_or_b32_e32 v149, s24, v11
	v_mov_b32_e32 v137, v133
	v_add_u32_e32 v138, v1, v10
	v_mov_b32_e32 v139, v133
	v_mov_b64_e32 v[140:141], 0x240
	v_mov_b64_e32 v[142:143], 0x23f
	v_add_u32_e32 v150, s50, v148
	v_add_u32_e32 v151, s51, v148
	v_add_u32_e32 v152, 0, v0
	s_barrier
	s_branch .LBB0_638

; #define PG8_STAGE(bufoff, gbase, voff) do { _Pragma("unroll") for (int _i = 0; _i < 2; ++_i) \
;         __builtin_amdgcn_global_load_lds((const unsigned*)((const char*)(gbase) + (voff)[_i]), (LAS unsigned*)(lds + (bufoff) + ldsw + _i * 8192), 16, 0, 0); } while (0)
; #define PG8_WAIT_V(n) asm volatile("s_waitcnt vmcnt(" #n ")" ::: "memory")
; #define PG8_BAR __builtin_amdgcn_s_barrier()
; template <class Epi>
; __device__ __forceinline__ void gemm_phase(LAS unsigned char* lds, const Gemm g, const StaticOrder& S, const Epi& E) {
;     ...
;     PG8_STAGE(PG8_SB(0, 0), cB, voffB); PG8_STAGE(PG8_SB(0, 1), cB + hsB, voffB); PG8_STAGE(PG8_SA(0, 0), cA, voffA); PG8_STAGE(PG8_SA(0, 1), cA + hsA, voffA);
;     if (wr == 1) PG8_BAR;
;     PG8_WAIT_V(2); PG8_BAR;
;     PG8_STAGE(PG8_SB(1, 0), cB + kstep, voffB); PG8_STAGE(PG8_SA(1, 0), cA + kstep, voffA); PG8_STAGE(PG8_SB(1, 1), cB + hsB + kstep, voffB);
;     PG8_WAIT_V(6); PG8_BAR;
.LBB0_834:
	s_mov_b64 s[28:29], 0x80
	s_and_b32 s6, s0, 3
	s_add_i32 m0, s51, 0x18000
	v_lshl_add_u64 v[6:7], v[6:7], 0, s[28:29]
	s_lshl_b32 s58, s1, 6
	s_lshl_b32 s5, s1, 13
	s_lshl_b32 s7, s6, 5
	s_lshl_b32 s10, s6, 12
	global_load_lds_dwordx4 v[6:7], off
	v_lshl_add_u64 v[2:3], v[2:3], 0, s[28:29]
	s_add_i32 m0, s51, 0x1a000
	s_add_i32 s59, s51, 0x8000
	s_add_i32 s68, s51, 0xa000
	global_load_lds_dwordx4 v[2:3], off
	v_lshl_add_u64 v[0:1], v[0:1], 0, s[28:29]
	s_mov_b32 m0, s59
	s_add_u32 s0, s30, 0x80080
	global_load_lds_dwordx4 v[0:1], off
	v_lshl_add_u64 v[0:1], v[4:5], 0, s[28:29]
	s_mov_b32 m0, s68
	s_addc_u32 s1, s31, 0
	global_load_lds_dwordx4 v[0:1], off
	s_add_i32 m0, s51, 0x1c000
	v_lshl_add_u64 v[0:1], s[0:1], 0, v[130:131]
	global_load_lds_dwordx4 v[0:1], off
	v_lshl_add_u64 v[0:1], s[0:1], 0, v[134:135]
	s_add_i32 m0, s51, 0x1e000
	s_cmpk_lt_u32 s4, 0x100
	global_load_lds_dwordx4 v[0:1], off
	s_waitcnt vmcnt(8)
	s_barrier
	v_bfe_u32 v1, v198, 4, 2
	s_cselect_b64 s[36:37], -1, 0
	s_cmp_lt_u32 s6, 2
	v_lshlrev_b32_e32 v0, 4, v1
	v_lshlrev_b32_e32 v5, 6, v198
	s_movk_i32 s0, 0x3c0
	s_cselect_b64 s[38:39], -1, 0
	s_cmp_eq_u32 s6, 0
	v_and_b32_e32 v162, 15, v198
	v_lshlrev_b32_e32 v3, 2, v198
	v_and_or_b32 v5, v5, s0, v0
	s_cselect_b64 s[0:1], -1, 0
	s_ashr_i32 s69, s63, 31
	s_ashr_i32 s70, s2, 31
	s_lshl_b32 s6, s6, 6
	v_lshl_or_b32 v2, v162, 6, v0
	v_and_b32_e32 v4, 32, v3
	s_add_u32 s6, s3, s6
	v_bitop3_b32 v2, v2, s5, v4 bitop3:0xde
	v_bitop3_b32 v163, s10, v5, v4 bitop3:0xf6
	v_lshl_or_b32 v164, v1, 3, s7
	v_cmp_gt_u32_e64 s[10:11], 2, v1
	v_cmp_eq_u32_e64 s[4:5], 0, v1
	s_addc_u32 s7, s60, 0
	v_mov_b32_e32 v1, v137
	v_lshl_add_u64 v[140:141], s[6:7], 0, v[0:1]
	v_lshlrev_b32_e32 v0, 9, v198
	v_and_b32_e32 v0, 0x70000, v0
	v_lshlrev_b32_e32 v1, 12, v10
	v_or3_b32 v0, v8, v0, v1
	v_add_u32_e32 v142, v0, v9
	v_lshlrev_b32_e32 v0, 5, v11
	v_and_b32_e32 v0, 0xf0000, v0
	s_waitcnt vmcnt(6)
	v_readlane_b32 s34, v247, 18
	v_or3_b32 v0, v8, v0, v1
	v_and_b32_e32 v136, 64, v3
	v_readlane_b32 s35, v247, 19
	v_add_u32_e32 v144, v0, v9
	s_add_i32 s71, 0, 0x10000
	s_add_i32 s72, 0, 0x14000
	v_mbcnt_lo_u32_b32 v0, -1, 0
	v_or_b32_e32 v165, 0xfffffc00, v164
	v_or_b32_e32 v166, 16, v162
	v_or_b32_e32 v167, 32, v162
	v_or_b32_e32 v168, 48, v162
	v_lshl_add_u64 v[138:139], s[34:35], 0, v[136:137]
	v_mov_b32_e32 v143, v137
	v_mov_b32_e32 v145, v137
	v_mov_b64_e32 v[146:147], 0x3a8
	v_mov_b64_e32 v[148:149], 0x3a7
	v_add_u32_e32 v169, s71, v163
	v_add_u32_e32 v170, s72, v163
	v_add_u32_e32 v171, 0, v2
	s_mov_b32 s73, 0x28000
	s_mov_b64 s[40:41], 0x2c000
	s_mov_b32 s74, 0x2c000
	v_mbcnt_hi_u32_b32 v172, -1, v0
	s_barrier
	s_branch .LBB0_837

; #define PG8_STAGE(bufoff, gbase, voff) do { _Pragma("unroll") for (int _i = 0; _i < 2; ++_i) \
;         __builtin_amdgcn_global_load_lds((const unsigned*)((const char*)(gbase) + (voff)[_i]), (LAS unsigned*)(lds + (bufoff) + ldsw + _i * 8192), 16, 0, 0); } while (0)
; #define PG8_WAIT_V(n) asm volatile("s_waitcnt vmcnt(" #n ")" ::: "memory")
; #define PG8_BAR __builtin_amdgcn_s_barrier()
; template <class Epi>
; __device__ __forceinline__ void gemm_phase(LAS unsigned char* lds, const Gemm g, const StaticOrder& S, const Epi& E) {
;     ...
;     PG8_STAGE(PG8_SB(0, 0), cB, voffB); PG8_STAGE(PG8_SB(0, 1), cB + hsB, voffB); PG8_STAGE(PG8_SA(0, 0), cA, voffA); PG8_STAGE(PG8_SA(0, 1), cA + hsA, voffA);
;     if (wr == 1) PG8_BAR;
;     PG8_WAIT_V(2); PG8_BAR;
;     PG8_STAGE(PG8_SB(1, 0), cB + kstep, voffB); PG8_STAGE(PG8_SA(1, 0), cA + kstep, voffA); PG8_STAGE(PG8_SB(1, 1), cB + hsB + kstep, voffB);
;     PG8_WAIT_V(6); PG8_BAR;
.LBB0_946:
	s_mov_b64 s[26:27], 0x80
	s_and_b32 s54, s1, 3
	s_add_i32 m0, s49, 0x18000
	v_lshl_add_u64 v[6:7], v[6:7], 0, s[26:27]
	s_lshl_b32 s55, s0, 6
	s_lshl_b32 s5, s0, 13
	s_lshl_b32 s7, s54, 12
	global_load_lds_dwordx4 v[6:7], off
	v_lshl_add_u64 v[4:5], v[4:5], 0, s[26:27]
	s_add_i32 m0, s49, 0x1a000
	s_add_i32 s56, s49, 0x8000
	s_add_i32 s57, s49, 0xa000
	global_load_lds_dwordx4 v[4:5], off
	v_lshl_add_u64 v[0:1], v[0:1], 0, s[26:27]
	s_mov_b32 m0, s56
	s_add_u32 s0, s34, 0x20080
	global_load_lds_dwordx4 v[0:1], off
	v_lshl_add_u64 v[0:1], v[2:3], 0, s[26:27]
	s_mov_b32 m0, s57
	s_addc_u32 s1, s35, 0
	global_load_lds_dwordx4 v[0:1], off
	s_add_i32 m0, s49, 0x1c000
	v_lshl_add_u64 v[0:1], s[0:1], 0, v[130:131]
	global_load_lds_dwordx4 v[0:1], off
	v_lshl_add_u64 v[0:1], s[0:1], 0, v[134:135]
	s_add_i32 m0, s49, 0x1e000
	v_lshlrev_b32_e32 v4, 2, v160
	global_load_lds_dwordx4 v[0:1], off
	s_waitcnt vmcnt(8)
	s_barrier
	v_bfe_u32 v1, v198, 4, 2
	v_lshlrev_b32_e32 v2, 4, v1
	v_lshlrev_b32_e32 v0, 3, v1
	v_lshl_or_b32 v3, v160, 6, v2
	v_or_b32_e32 v2, v2, v159
	v_cmp_gt_u32_e64 s[0:1], 2, v1
	v_lshlrev_b32_e32 v1, 7, v198
	v_bitop3_b32 v162, s7, v2, v161 bitop3:0xf6
	v_and_b32_e32 v1, 0x1c000, v1
	v_lshlrev_b32_e32 v2, 10, v156
	v_or3_b32 v1, v154, v1, v2
	s_cmpk_lt_u32 s8, 0x100
	v_readlane_b32 s8, v247, 18
	v_add_u32_e32 v140, v1, v155
	v_lshlrev_b32_e32 v1, 3, v158
	v_and_b32_e32 v4, 32, v4
	s_waitcnt vmcnt(6)
	v_and_b32_e32 v136, 64, v8
	v_readlane_b32 s9, v247, 19
	v_and_b32_e32 v1, 0x3c000, v1
	v_bitop3_b32 v3, v3, s5, v4 bitop3:0xde
	s_cselect_b64 s[28:29], -1, 0
	v_lshl_add_u64 v[138:139], s[8:9], 0, v[136:137]
	v_or3_b32 v1, v154, v1, v2
	s_add_i32 s69, 0, 0x10000
	s_add_i32 s70, 0, 0x14000
	v_lshlrev_b32_e32 v136, 1, v0
	v_mbcnt_lo_u32_b32 v0, -1, 0
	v_or_b32_e32 v163, 16, v160
	v_or_b32_e32 v164, 32, v160
	v_or_b32_e32 v165, 48, v160
	s_ashr_i32 s58, s63, 31
	s_ashr_i32 s59, s2, 31
	v_mov_b32_e32 v141, v137
	v_add_u32_e32 v142, v1, v155
	v_mov_b32_e32 v143, v137
	v_mov_b64_e32 v[144:145], 0x300
	v_mov_b64_e32 v[146:147], 0x2ff
	s_movk_i32 s68, 0x61
	v_add_u32_e32 v166, s69, v162
	v_add_u32_e32 v167, s70, v162
	v_add_u32_e32 v168, 0, v3
	v_mov_b32_e32 v169, 0x358637bd
	s_movk_i32 s71, 0x1800
	v_mbcnt_hi_u32_b32 v170, -1, v0
	s_barrier
	s_branch .LBB0_949

; #define PG8_STAGE(bufoff, gbase, voff) do { _Pragma("unroll") for (int _i = 0; _i < 2; ++_i) \
;         __builtin_amdgcn_global_load_lds((const unsigned*)((const char*)(gbase) + (voff)[_i]), (LAS unsigned*)(lds + (bufoff) + ldsw + _i * 8192), 16, 0, 0); } while (0)
; #define PG8_WAIT_V(n) asm volatile("s_waitcnt vmcnt(" #n ")" ::: "memory")
; #define PG8_BAR __builtin_amdgcn_s_barrier()
; template <class Epi>
; __device__ __forceinline__ void gemm_phase(LAS unsigned char* lds, const Gemm g, const StaticOrder& S, const Epi& E) {
;     const int tid = threadIdx.x, wid = __builtin_amdgcn_readfirstlane(tid >> 6), lane = tid & 63, wr = wid >> 2, wc = wid & 3, fr = lane & 15, fq = lane >> 4;
;     const int K = g.K, nt = K / BK;
;     unsigned voffA[2], voffB[2];
; #pragma unroll
;     for (int i = 0; i < 2; ++i) { int R, C; stage_rc(tid * 16 + i * 8192, R, C); const int Rb = Epi::PERM ? ((R & ~31) + perm32(R & 31)) : R;
;         voffA[i] = (unsigned)(R * g.lda + C) * 2u; voffB[i] = (unsigned)(Rb * g.ldb + C) * 2u; }
;     const size_t kstep = (size_t)(BK * 2);
;     const size_t hsA = (size_t)HALF * g.lda * 2, hsB = (size_t)HALF * g.ldb * 2;
;     const size_t tsA = 2 * hsA, tsB = 2 * hsB;
;     const unsigned ldsw = (unsigned)wid * 1024u;
;     const int aoff = lds_byte(wr * 64 + fr, fq * 8), boff = lds_byte(wc * 32 + fr, fq * 8);
;     ...
;     PG8_STAGE(PG8_SB(0, 0), cB, voffB); PG8_STAGE(PG8_SB(0, 1), cB + hsB, voffB); PG8_STAGE(PG8_SA(0, 0), cA, voffA); PG8_STAGE(PG8_SA(0, 1), cA + hsA, voffA);
;     if (wr == 1) PG8_BAR;
;     PG8_WAIT_V(2); PG8_BAR;
;     PG8_STAGE(PG8_SB(1, 0), cB + kstep, voffB); PG8_STAGE(PG8_SA(1, 0), cA + kstep, voffA); PG8_STAGE(PG8_SB(1, 1), cB + hsB + kstep, voffB);
;     PG8_WAIT_V(6); PG8_BAR;
.LBB0_994:
	s_add_u32 s6, s84, 0x92000
	s_addc_u32 s7, s85, 0
	s_lshl_b32 s8, s8, 5
	s_and_b32 s26, s8, 0x60
	s_mov_b64 s[8:9], 0x80
	s_add_i32 m0, s31, 0x18000
	v_lshl_add_u64 v[6:7], v[6:7], 0, s[8:9]
	s_lshl_b32 s23, s22, 13
	s_lshl_b32 s27, s26, 7
	global_load_lds_dwordx4 v[6:7], off
	v_lshl_add_u64 v[4:5], v[4:5], 0, s[8:9]
	s_add_i32 m0, s31, 0x1a000
	s_add_i32 s57, s31, 0x8000
	s_add_i32 s58, s31, 0xa000
	global_load_lds_dwordx4 v[4:5], off
	v_lshl_add_u64 v[0:1], v[0:1], 0, s[8:9]
	s_mov_b32 m0, s57
	s_add_u32 s24, s46, 0x20080
	global_load_lds_dwordx4 v[0:1], off
	v_lshl_add_u64 v[0:1], v[2:3], 0, s[8:9]
	s_mov_b32 m0, s58
	s_addc_u32 s25, s47, 0
	global_load_lds_dwordx4 v[0:1], off
	s_add_i32 m0, s31, 0x1c000
	v_lshl_add_u64 v[0:1], s[24:25], 0, v[130:131]
	global_load_lds_dwordx4 v[0:1], off
	v_lshl_add_u64 v[0:1], s[24:25], 0, v[134:135]
	s_add_i32 m0, s31, 0x1e000
	v_lshlrev_b32_e32 v2, 2, v160
	global_load_lds_dwordx4 v[0:1], off
	s_waitcnt vmcnt(8)
	s_barrier
	v_lshlrev_b32_e32 v0, 1, v157
	v_lshl_or_b32 v1, v160, 6, v0
	v_or_b32_e32 v0, v0, v159
	v_and_b32_e32 v2, 32, v2
	v_bitop3_b32 v151, s27, v0, v161 bitop3:0xf6
	v_lshlrev_b32_e32 v0, 7, v198
	v_bitop3_b32 v1, v1, s23, v2 bitop3:0xde
	v_and_b32_e32 v0, 0x1c000, v0
	v_lshlrev_b32_e32 v2, 10, v156
	v_or3_b32 v0, v154, v0, v2
	v_add_u32_e32 v136, v0, v155
	v_lshlrev_b32_e32 v0, 3, v158
	s_waitcnt vmcnt(6)
	s_cmpk_lt_u32 s1, 0x100
	v_and_b32_e32 v0, 0x3c000, v0
	v_lshl_or_b32 v150, s22, 6, v160
	s_cselect_b64 s[22:23], -1, 0
	v_or3_b32 v0, v154, v0, v2
	s_add_i32 s66, 0, 0x10000
	s_add_i32 s67, 0, 0x14000
	s_sext_i32_i8 s68, s0
	s_ashr_i32 s59, s63, 31
	v_or_b32_e32 v152, s26, v157
	v_mov_b32_e32 v137, v131
	v_add_u32_e32 v138, v0, v155
	v_mov_b32_e32 v139, v131
	v_mov_b64_e32 v[140:141], 0x480
	v_mov_b64_e32 v[142:143], 0x47f
	v_add_u32_e32 v153, s66, v151
	v_add_u32_e32 v154, s67, v151
	v_add_u32_e32 v155, 0, v1
	v_mov_b32_e32 v156, 0x358637bd
	s_mov_b64 s[24:25], 0x80000
	s_mov_b64 s[26:27], 0x90000
	s_mov_b64 s[28:29], 0xa0000
	s_mov_b64 s[36:37], 0xb0000
	s_barrier
	s_branch .LBB0_997

; #define PG8_STAGE(bufoff, gbase, voff) do { _Pragma("unroll") for (int _i = 0; _i < 2; ++_i) \
;         __builtin_amdgcn_global_load_lds((const unsigned*)((const char*)(gbase) + (voff)[_i]), (LAS unsigned*)(lds + (bufoff) + ldsw + _i * 8192), 16, 0, 0); } while (0)
; #define PG8_WAIT_V(n) asm volatile("s_waitcnt vmcnt(" #n ")" ::: "memory")
; #define PG8_BAR __builtin_amdgcn_s_barrier()
; template <class Epi>
; __device__ __forceinline__ void gemm_phase(LAS unsigned char* lds, const Gemm g, const StaticOrder& S, const Epi& E) {
;     const int tid = threadIdx.x, wid = __builtin_amdgcn_readfirstlane(tid >> 6), lane = tid & 63, wr = wid >> 2, wc = wid & 3, fr = lane & 15, fq = lane >> 4;
;     const int K = g.K, nt = K / BK;
;     unsigned voffA[2], voffB[2];
; #pragma unroll
;     for (int i = 0; i < 2; ++i) { int R, C; stage_rc(tid * 16 + i * 8192, R, C); const int Rb = Epi::PERM ? ((R & ~31) + perm32(R & 31)) : R;
;         voffA[i] = (unsigned)(R * g.lda + C) * 2u; voffB[i] = (unsigned)(Rb * g.ldb + C) * 2u; }
;     const size_t kstep = (size_t)(BK * 2);
;     const size_t hsA = (size_t)HALF * g.lda * 2, hsB = (size_t)HALF * g.ldb * 2;
;     const size_t tsA = 2 * hsA, tsB = 2 * hsB;
;     const unsigned ldsw = (unsigned)wid * 1024u;
;     const int aoff = lds_byte(wr * 64 + fr, fq * 8), boff = lds_byte(wc * 32 + fr, fq * 8);
;     ...
;     PG8_STAGE(PG8_SB(0, 0), cB, voffB); PG8_STAGE(PG8_SB(0, 1), cB + hsB, voffB); PG8_STAGE(PG8_SA(0, 0), cA, voffA); PG8_STAGE(PG8_SA(0, 1), cA + hsA, voffA);
;     if (wr == 1) PG8_BAR;
;     PG8_WAIT_V(2); PG8_BAR;
;     PG8_STAGE(PG8_SB(1, 0), cB + kstep, voffB); PG8_STAGE(PG8_SA(1, 0), cA + kstep, voffA); PG8_STAGE(PG8_SB(1, 1), cB + hsB + kstep, voffB);
;     PG8_WAIT_V(6); PG8_BAR;
.LBB0_1221:
	s_lshl_b32 s10, s10, 5
	s_and_b32 s16, s10, 0x60
	s_mov_b64 s[10:11], 0x80
	s_add_i32 m0, s35, 0x18000
	v_lshl_add_u64 v[6:7], v[6:7], 0, s[10:11]
	s_lshl_b32 s13, s1, 13
	s_lshl_b32 s17, s16, 7
	global_load_lds_dwordx4 v[6:7], off
	v_lshl_add_u64 v[2:3], v[2:3], 0, s[10:11]
	s_add_i32 m0, s35, 0x1a000
	s_add_i32 s47, s35, 0x8000
	s_add_i32 s48, s35, 0xa000
	global_load_lds_dwordx4 v[2:3], off
	v_lshl_add_u64 v[0:1], v[0:1], 0, s[10:11]
	s_mov_b32 m0, s47
	s_add_u32 s14, s38, 0x80080
	global_load_lds_dwordx4 v[0:1], off
	v_lshl_add_u64 v[0:1], v[4:5], 0, s[10:11]
	s_mov_b32 m0, s48
	s_addc_u32 s15, s39, 0
	global_load_lds_dwordx4 v[0:1], off
	s_add_i32 m0, s35, 0x1c000
	v_lshl_add_u64 v[0:1], s[14:15], 0, v[130:131]
	global_load_lds_dwordx4 v[0:1], off
	v_lshl_add_u64 v[0:1], s[14:15], 0, v[134:135]
	s_add_i32 m0, s35, 0x1e000
	s_sext_i32_i8 s56, s0
	global_load_lds_dwordx4 v[0:1], off
	s_waitcnt vmcnt(8)
	s_barrier
	v_and_b32_e32 v0, 15, v198
	v_lshlrev_b32_e32 v1, 1, v11
	v_lshlrev_b32_e32 v2, 2, v198
	v_lshlrev_b32_e32 v3, 6, v198
	s_movk_i32 s0, 0x3c0
	v_lshl_or_b32 v146, s1, 6, v0
	v_lshl_or_b32 v0, v0, 6, v1
	v_and_b32_e32 v2, 32, v2
	v_and_or_b32 v1, v3, s0, v1
	v_bitop3_b32 v147, s17, v1, v2 bitop3:0xf6
	v_lshlrev_b32_e32 v1, 9, v198
	v_bitop3_b32 v0, v0, s13, v2 bitop3:0xde
	v_and_b32_e32 v1, 0x70000, v1
	v_lshlrev_b32_e32 v2, 12, v10
	v_or3_b32 v1, v8, v1, v2
	v_add_u32_e32 v136, v1, v9
	v_lshlrev_b32_e32 v1, 5, v12
	s_waitcnt vmcnt(6)
	s_cmpk_lt_u32 s12, 0x100
	v_and_b32_e32 v1, 0xf0000, v1
	s_cselect_b64 s[12:13], -1, 0
	v_or3_b32 v1, v8, v1, v2
	s_add_i32 s50, 0, 0x10000
	s_add_i32 s51, 0, 0x14000
	s_ashr_i32 s49, s63, 31
	v_or_b32_e32 v148, s16, v11
	v_mov_b32_e32 v137, v131
	v_add_u32_e32 v138, v1, v9
	v_mov_b32_e32 v139, v131
	v_mov_b64_e32 v[140:141], 0x200
	v_mov_b64_e32 v[142:143], 0x1ff
	v_add_u32_e32 v149, s50, v147
	v_add_u32_e32 v150, s51, v147
	v_add_u32_e32 v151, 0, v0
	s_mov_b32 s52, 0x80000
	s_mov_b64 s[14:15], 0x90000
	s_mov_b32 s53, 0x90000
	s_mov_b64 s[16:17], 0xa0000
	s_mov_b32 s54, 0xa0000
	s_mov_b64 s[22:23], 0xb0000
	s_mov_b32 s55, 0xb0000
	s_barrier
	s_branch .LBB0_1224
